# P0: w_in transposition loads issued 32 at a time instead of one per wait
# speedup vs baseline: 1.0435x; 1.0027x over previous
; __device__ __forceinline__ int map_win(int db) { if (db < 144) return db * 32; if (db < 208) return db * 32 + 64; const int t = db - 208; return t == 0 ? 4608 : (t == 4 ? 4640 : -1); }
; __device__ __forceinline__ void tr_item(const float* W, int K, int N, bf16* WT, int kb, int drow0, int n0, const float* gain, LAS float* scr, int lane) {
;     ...
;     for (int i = 0; i < 32; ++i) { const int kk = 2 * i + (lane >> 5); float v = 0.f;
;         if (n0 >= 0) { v = W[(size_t)(k0 + kk) * N + n0 + (lane & 31)]; if (gain) v *= gain[k0 + kk]; }
;         scr[kk * 33 + (lane & 31)] = v; }
; __device__ __forceinline__ void p0_prologue(const Params& p, LAS unsigned char* lds) {
;     ...
;           if (r < I0) { const int kb = r / 216, db = r % 216; tr_item(p.w_in, 1024, 6720, (bf16*)(ws + W_IN), kb, db * 32, map_win(db), nullptr, scr, lane); continue; } r -= I0;
.LBB0_115:
	v_mov_b32_e32 v95, 0
	v_mov_b32_e32 v96, 0
	v_mov_b32_e32 v97, 0
	v_mov_b32_e32 v98, 0
	v_mov_b32_e32 v99, 0
	v_mov_b32_e32 v100, 0
	v_mov_b32_e32 v101, 0
	v_mov_b32_e32 v102, 0
	v_mov_b32_e32 v103, 0
	v_mov_b32_e32 v104, 0
	v_mov_b32_e32 v105, 0
	v_mov_b32_e32 v106, 0
	v_mov_b32_e32 v107, 0
	v_mov_b32_e32 v108, 0
	v_mov_b32_e32 v109, 0
	v_mov_b32_e32 v110, 0
	v_mov_b32_e32 v111, 0
	v_mov_b32_e32 v112, 0
	v_mov_b32_e32 v113, 0
	v_mov_b32_e32 v114, 0
	v_mov_b32_e32 v115, 0
	v_mov_b32_e32 v116, 0
	v_mov_b32_e32 v117, 0
	v_mov_b32_e32 v118, 0
	v_mov_b32_e32 v119, 0
	v_mov_b32_e32 v120, 0
	v_mov_b32_e32 v121, 0
	v_mov_b32_e32 v122, 0
	v_mov_b32_e32 v123, 0
	v_mov_b32_e32 v124, 0
	v_mov_b32_e32 v125, 0
	v_mov_b32_e32 v126, 0
	s_and_saveexec_b64 s[14:15], vcc
	s_cbranch_execz .Ltrwin_skip
	v_lshl_add_u64 v[64:65], v[62:63], 0, s[12:13]
	global_load_dword v95, v[64:65], off
	v_lshl_add_u64 v[64:65], v[60:61], 0, s[12:13]
	global_load_dword v96, v[64:65], off
	v_lshl_add_u64 v[64:65], v[58:59], 0, s[12:13]
	global_load_dword v97, v[64:65], off
	v_lshl_add_u64 v[64:65], v[56:57], 0, s[12:13]
	global_load_dword v98, v[64:65], off
	v_lshl_add_u64 v[64:65], v[54:55], 0, s[12:13]
	global_load_dword v99, v[64:65], off
	v_lshl_add_u64 v[64:65], v[52:53], 0, s[12:13]
	global_load_dword v100, v[64:65], off
	v_lshl_add_u64 v[64:65], v[46:47], 0, s[12:13]
	global_load_dword v101, v[64:65], off
	v_lshl_add_u64 v[64:65], v[44:45], 0, s[12:13]
	global_load_dword v102, v[64:65], off
	s_add_u32 s12, s12, 0x69000
	s_addc_u32 s13, s13, 0
	v_lshl_add_u64 v[64:65], v[62:63], 0, s[12:13]
	global_load_dword v103, v[64:65], off
	v_lshl_add_u64 v[64:65], v[60:61], 0, s[12:13]
	global_load_dword v104, v[64:65], off
	v_lshl_add_u64 v[64:65], v[58:59], 0, s[12:13]
	global_load_dword v105, v[64:65], off
	v_lshl_add_u64 v[64:65], v[56:57], 0, s[12:13]
	global_load_dword v106, v[64:65], off
	v_lshl_add_u64 v[64:65], v[54:55], 0, s[12:13]
	global_load_dword v107, v[64:65], off
	v_lshl_add_u64 v[64:65], v[52:53], 0, s[12:13]
	global_load_dword v108, v[64:65], off
	v_lshl_add_u64 v[64:65], v[46:47], 0, s[12:13]
	global_load_dword v109, v[64:65], off
	v_lshl_add_u64 v[64:65], v[44:45], 0, s[12:13]
	global_load_dword v110, v[64:65], off
	s_add_u32 s12, s12, 0x69000
	s_addc_u32 s13, s13, 0
	v_lshl_add_u64 v[64:65], v[62:63], 0, s[12:13]
	global_load_dword v111, v[64:65], off
	v_lshl_add_u64 v[64:65], v[60:61], 0, s[12:13]
	global_load_dword v112, v[64:65], off
	v_lshl_add_u64 v[64:65], v[58:59], 0, s[12:13]
	global_load_dword v113, v[64:65], off
	v_lshl_add_u64 v[64:65], v[56:57], 0, s[12:13]
	global_load_dword v114, v[64:65], off
	v_lshl_add_u64 v[64:65], v[54:55], 0, s[12:13]
	global_load_dword v115, v[64:65], off
	v_lshl_add_u64 v[64:65], v[52:53], 0, s[12:13]
	global_load_dword v116, v[64:65], off
	v_lshl_add_u64 v[64:65], v[46:47], 0, s[12:13]
	global_load_dword v117, v[64:65], off
	v_lshl_add_u64 v[64:65], v[44:45], 0, s[12:13]
	global_load_dword v118, v[64:65], off
	s_add_u32 s12, s12, 0x69000
	s_addc_u32 s13, s13, 0
	v_lshl_add_u64 v[64:65], v[62:63], 0, s[12:13]
	global_load_dword v119, v[64:65], off
	v_lshl_add_u64 v[64:65], v[60:61], 0, s[12:13]
	global_load_dword v120, v[64:65], off
	v_lshl_add_u64 v[64:65], v[58:59], 0, s[12:13]
	global_load_dword v121, v[64:65], off
	v_lshl_add_u64 v[64:65], v[56:57], 0, s[12:13]
	global_load_dword v122, v[64:65], off
	v_lshl_add_u64 v[64:65], v[54:55], 0, s[12:13]
	global_load_dword v123, v[64:65], off
	v_lshl_add_u64 v[64:65], v[52:53], 0, s[12:13]
	global_load_dword v124, v[64:65], off
	v_lshl_add_u64 v[64:65], v[46:47], 0, s[12:13]
	global_load_dword v125, v[64:65], off
	v_lshl_add_u64 v[64:65], v[44:45], 0, s[12:13]
	global_load_dword v126, v[64:65], off
	s_add_u32 s12, s12, 0x69000
	s_addc_u32 s13, s13, 0
.Ltrwin_skip:
	s_or_b64 exec, exec, s[14:15]
	s_waitcnt vmcnt(0)
	ds_write_b32 v4, v95
	ds_write_b32 v4, v96 offset:264
	ds_write_b32 v4, v97 offset:528
	ds_write_b32 v4, v98 offset:792
	ds_write_b32 v4, v99 offset:1056
	ds_write_b32 v4, v100 offset:1320
	ds_write_b32 v4, v101 offset:1584
	ds_write_b32 v4, v102 offset:1848
	v_add_u32_e32 v4, 0x840, v4
	ds_write_b32 v4, v103
	ds_write_b32 v4, v104 offset:264
	ds_write_b32 v4, v105 offset:528
	ds_write_b32 v4, v106 offset:792
	ds_write_b32 v4, v107 offset:1056
	ds_write_b32 v4, v108 offset:1320
	ds_write_b32 v4, v109 offset:1584
	ds_write_b32 v4, v110 offset:1848
	v_add_u32_e32 v4, 0x840, v4
	ds_write_b32 v4, v111
	ds_write_b32 v4, v112 offset:264
	ds_write_b32 v4, v113 offset:528
	ds_write_b32 v4, v114 offset:792
	ds_write_b32 v4, v115 offset:1056
	ds_write_b32 v4, v116 offset:1320
	ds_write_b32 v4, v117 offset:1584
	ds_write_b32 v4, v118 offset:1848
	v_add_u32_e32 v4, 0x840, v4
	ds_write_b32 v4, v119
	ds_write_b32 v4, v120 offset:264
	ds_write_b32 v4, v121 offset:528
	ds_write_b32 v4, v122 offset:792
	ds_write_b32 v4, v123 offset:1056
	ds_write_b32 v4, v124 offset:1320
	ds_write_b32 v4, v125 offset:1584
	ds_write_b32 v4, v126 offset:1848
	v_add_u32_e32 v4, 0x840, v4
	s_branch .LBB0_24
